# in-proj GEMM rewritten by hand: 256x128x64 tiles, LDS-DMA single stage, register-resident fragments
# speedup vs baseline: 1.0527x; 1.0527x over previous
.LBB0_270:
	s_and_b64 s[0:1], s[20:21], exec
	s_mov_b32 s10, 208
	s_mov_b32 s11, 20648882
	s_mov_b32 s12, 6656
	s_mov_b32 s1, 2496
	s_cmov_b32 s10, 168
	s_cmov_b32 s11, 25565282
	s_cmov_b32 s12, 5376
	s_cmov_b32 s1, 2016
	v_readlane_b32 s28, v252, 0
	v_readlane_b32 s6, v252, 1
	s_lshr_b32 s6, s6, 3
	s_and_b32 s0, s28, 7
	s_mul_i32 s0, s0, s6
	s_lshr_b32 s28, s28, 3
	s_add_u32 s0, s0, s28
	s_lshl_b32 s6, s6, 3
	s_cmp_ge_u32 s0, s1
	s_cbranch_scc1 .Lgin_done
	v_and_b32_e32 v128, 31, v193
	v_lshlrev_b32_e32 v129, 7, v128
	v_bfe_u32 v130, v193, 1, 3
	v_bfe_u32 v131, v193, 5, 1
	v_xor_b32_e32 v130, v130, v131
	v_bfe_u32 v131, v193, 7, 1
	v_lshl_add_u32 v131, v131, 14, v129
	v_bfe_u32 v132, v193, 6, 1
	v_lshl_add_u32 v132, v132, 13, v129
	v_lshl_add_u32 v144, v130, 4, v131
	v_lshl_add_u32 v211, v130, 4, v132
	v_xor_b32_e32 v128, 2, v130
	v_lshl_add_u32 v146, v128, 4, v131
	v_lshl_add_u32 v248, v128, 4, v132
	v_xor_b32_e32 v128, 4, v130
	v_lshl_add_u32 v147, v128, 4, v131
	v_lshl_add_u32 v249, v128, 4, v132
	v_xor_b32_e32 v128, 6, v130
	v_lshl_add_u32 v210, v128, 4, v131
	v_lshl_add_u32 v250, v128, 4, v132
	v_and_b32_e32 v128, 7, v193
	v_bfe_u32 v129, v193, 4, 3
	v_xor_b32_e32 v128, v128, v129
	v_lshrrev_b32_e32 v129, 3, v193
	v_lshlrev_b32_e32 v129, 11, v129
	v_lshl_add_u32 v251, v128, 4, v129
	v_lshrrev_b32_e32 v128, 6, v193
	v_lshlrev_b32_e32 v128, 10, v128
	s_nop 0
	v_readfirstlane_b32 s22, v128
.Lgin_tile:
	s_mul_hi_u32 s28, s0, s11
	s_mul_i32 vcc_lo, s28, s10
	s_sub_u32 vcc_lo, s0, vcc_lo
	s_lshr_b32 vcc_hi, vcc_lo, 3
	s_and_b32 vcc_lo, vcc_lo, 7
	s_lshl_b32 s28, s28, 3
	s_add_u32 s28, s28, vcc_lo
	s_lshl_b32 s20, s28, 19
	s_add_u32 s20, s20, 29876224
	s_add_u32 s20, s94, s20
	s_addc_u32 s21, s95, 0
	s_lshl_b32 s24, vcc_hi, 18
	s_add_u32 s24, s94, s24
	s_addc_u32 s25, s95, 0
	s_mul_i32 s26, s28, s12
	s_lshl_b32 s26, s26, 8
	s_lshl_b32 vcc_hi, vcc_hi, 8
	s_add_u32 s26, s26, vcc_hi
	s_add_u32 s26, s34, s26
	s_addc_u32 s27, s35, 0
	s_mov_b32 m0, s22
	s_nop 0
	global_load_lds_dwordx4 v251, s[20:21]
	s_add_u32 m0, m0, 0x1000
	s_add_u32 s20, s20, 0x10000
	s_addc_u32 s21, s21, 0
	global_load_lds_dwordx4 v251, s[20:21]
	s_add_u32 m0, m0, 0x1000
	s_add_u32 s20, s20, 0x10000
	s_addc_u32 s21, s21, 0
	global_load_lds_dwordx4 v251, s[20:21]
	s_add_u32 m0, m0, 0x1000
	s_add_u32 s20, s20, 0x10000
	s_addc_u32 s21, s21, 0
	global_load_lds_dwordx4 v251, s[20:21]
	s_add_u32 m0, m0, 0x1000
	s_add_u32 s20, s20, 0x10000
	s_addc_u32 s21, s21, 0
	global_load_lds_dwordx4 v251, s[20:21]
	s_add_u32 m0, m0, 0x1000
	s_add_u32 s20, s20, 0x10000
	s_addc_u32 s21, s21, 0
	global_load_lds_dwordx4 v251, s[20:21]
	s_add_u32 m0, m0, 0x1000
	s_add_u32 s20, s20, 0x10000
	s_addc_u32 s21, s21, 0
	global_load_lds_dwordx4 v251, s[20:21]
	s_add_u32 m0, m0, 0x1000
	s_add_u32 s20, s20, 0x10000
	s_addc_u32 s21, s21, 0
	global_load_lds_dwordx4 v251, s[20:21]
	s_add_u32 m0, m0, 0x1000
	s_sub_u32 s20, s20, 458624
	s_subb_u32 s21, s21, 0
	global_load_lds_dwordx4 v251, s[24:25]
	s_add_u32 m0, m0, 0x1000
	s_add_u32 s24, s24, 0x10000
	s_addc_u32 s25, s25, 0
	global_load_lds_dwordx4 v251, s[24:25]
	s_add_u32 m0, m0, 0x1000
	s_add_u32 s24, s24, 0x10000
	s_addc_u32 s25, s25, 0
	global_load_lds_dwordx4 v251, s[24:25]
	s_add_u32 m0, m0, 0x1000
	s_add_u32 s24, s24, 0x10000
	s_addc_u32 s25, s25, 0
	global_load_lds_dwordx4 v251, s[24:25]
	s_sub_u32 s24, s24, 196480
	s_subb_u32 s25, s25, 0
	v_mov_b32_e32 v0, 0
	v_mov_b32_e32 v1, 0
	v_mov_b32_e32 v2, 0
	v_mov_b32_e32 v3, 0
	v_mov_b32_e32 v4, 0
	v_mov_b32_e32 v5, 0
	v_mov_b32_e32 v6, 0
	v_mov_b32_e32 v7, 0
	v_mov_b32_e32 v8, 0
	v_mov_b32_e32 v9, 0
	v_mov_b32_e32 v10, 0
	v_mov_b32_e32 v11, 0
	v_mov_b32_e32 v12, 0
	v_mov_b32_e32 v13, 0
	v_mov_b32_e32 v14, 0
	v_mov_b32_e32 v15, 0
	v_mov_b32_e32 v16, 0
	v_mov_b32_e32 v17, 0
	v_mov_b32_e32 v18, 0
	v_mov_b32_e32 v19, 0
	v_mov_b32_e32 v20, 0
	v_mov_b32_e32 v21, 0
	v_mov_b32_e32 v22, 0
	v_mov_b32_e32 v23, 0
	v_mov_b32_e32 v24, 0
	v_mov_b32_e32 v25, 0
	v_mov_b32_e32 v26, 0
	v_mov_b32_e32 v27, 0
	v_mov_b32_e32 v28, 0
	v_mov_b32_e32 v29, 0
	v_mov_b32_e32 v30, 0
	v_mov_b32_e32 v31, 0
	v_mov_b32_e32 v32, 0
	v_mov_b32_e32 v33, 0
	v_mov_b32_e32 v34, 0
	v_mov_b32_e32 v35, 0
	v_mov_b32_e32 v36, 0
	v_mov_b32_e32 v37, 0
	v_mov_b32_e32 v38, 0
	v_mov_b32_e32 v39, 0
	v_mov_b32_e32 v40, 0
	v_mov_b32_e32 v41, 0
	v_mov_b32_e32 v42, 0
	v_mov_b32_e32 v43, 0
	v_mov_b32_e32 v44, 0
	v_mov_b32_e32 v45, 0
	v_mov_b32_e32 v46, 0
	v_mov_b32_e32 v47, 0
	v_mov_b32_e32 v48, 0
	v_mov_b32_e32 v49, 0
	v_mov_b32_e32 v50, 0
	v_mov_b32_e32 v51, 0
	v_mov_b32_e32 v52, 0
	v_mov_b32_e32 v53, 0
	v_mov_b32_e32 v54, 0
	v_mov_b32_e32 v55, 0
	v_mov_b32_e32 v56, 0
	v_mov_b32_e32 v57, 0
	v_mov_b32_e32 v58, 0
	v_mov_b32_e32 v59, 0
	v_mov_b32_e32 v60, 0
	v_mov_b32_e32 v61, 0
	v_mov_b32_e32 v62, 0
	v_mov_b32_e32 v63, 0
	v_mov_b32_e32 v64, 0
	v_mov_b32_e32 v65, 0
	v_mov_b32_e32 v66, 0
	v_mov_b32_e32 v67, 0
	v_mov_b32_e32 v68, 0
	v_mov_b32_e32 v69, 0
	v_mov_b32_e32 v70, 0
	v_mov_b32_e32 v71, 0
	v_mov_b32_e32 v72, 0
	v_mov_b32_e32 v73, 0
	v_mov_b32_e32 v74, 0
	v_mov_b32_e32 v75, 0
	v_mov_b32_e32 v76, 0
	v_mov_b32_e32 v77, 0
	v_mov_b32_e32 v78, 0
	v_mov_b32_e32 v79, 0
	v_mov_b32_e32 v80, 0
	v_mov_b32_e32 v81, 0
	v_mov_b32_e32 v82, 0
	v_mov_b32_e32 v83, 0
	v_mov_b32_e32 v84, 0
	v_mov_b32_e32 v85, 0
	v_mov_b32_e32 v86, 0
	v_mov_b32_e32 v87, 0
	v_mov_b32_e32 v88, 0
	v_mov_b32_e32 v89, 0
	v_mov_b32_e32 v90, 0
	v_mov_b32_e32 v91, 0
	v_mov_b32_e32 v92, 0
	v_mov_b32_e32 v93, 0
	v_mov_b32_e32 v94, 0
	v_mov_b32_e32 v95, 0
	v_mov_b32_e32 v96, 0
	v_mov_b32_e32 v97, 0
	v_mov_b32_e32 v98, 0
	v_mov_b32_e32 v99, 0
	v_mov_b32_e32 v100, 0
	v_mov_b32_e32 v101, 0
	v_mov_b32_e32 v102, 0
	v_mov_b32_e32 v103, 0
	v_mov_b32_e32 v104, 0
	v_mov_b32_e32 v105, 0
	v_mov_b32_e32 v106, 0
	v_mov_b32_e32 v107, 0
	v_mov_b32_e32 v108, 0
	v_mov_b32_e32 v109, 0
	v_mov_b32_e32 v110, 0
	v_mov_b32_e32 v111, 0
	v_mov_b32_e32 v112, 0
	v_mov_b32_e32 v113, 0
	v_mov_b32_e32 v114, 0
	v_mov_b32_e32 v115, 0
	v_mov_b32_e32 v116, 0
	v_mov_b32_e32 v117, 0
	v_mov_b32_e32 v118, 0
	v_mov_b32_e32 v119, 0
	v_mov_b32_e32 v120, 0
	v_mov_b32_e32 v121, 0
	v_mov_b32_e32 v122, 0
	v_mov_b32_e32 v123, 0
	v_mov_b32_e32 v124, 0
	v_mov_b32_e32 v125, 0
	v_mov_b32_e32 v126, 0
	v_mov_b32_e32 v127, 0
	s_mov_b32 s16, 16
.Lgin_k:
	s_waitcnt vmcnt(0)
	s_barrier
	ds_read_b128 v[216:219], v211 offset:32768
	ds_read_b128 v[232:235], v211 offset:36864
	ds_read_b128 v[128:131], v144 offset:0
	ds_read_b128 v[148:151], v144 offset:4096
	ds_read_b128 v[164:167], v144 offset:8192
	ds_read_b128 v[180:183], v144 offset:12288
	ds_read_b128 v[220:223], v248 offset:32768
	ds_read_b128 v[236:239], v248 offset:36864
	ds_read_b128 v[132:135], v146 offset:0
	ds_read_b128 v[152:155], v146 offset:4096
	ds_read_b128 v[168:171], v146 offset:8192
	ds_read_b128 v[184:187], v146 offset:12288
	ds_read_b128 v[224:227], v249 offset:32768
	ds_read_b128 v[240:243], v249 offset:36864
	ds_read_b128 v[136:139], v147 offset:0
	ds_read_b128 v[156:159], v147 offset:4096
	ds_read_b128 v[172:175], v147 offset:8192
	ds_read_b128 v[188:191], v147 offset:12288
	ds_read_b128 v[228:231], v250 offset:32768
	ds_read_b128 v[244:247], v250 offset:36864
	ds_read_b128 v[140:143], v210 offset:0
	ds_read_b128 v[160:163], v210 offset:4096
	ds_read_b128 v[176:179], v210 offset:8192
	ds_read_b128 v[212:215], v210 offset:12288
	s_waitcnt lgkmcnt(0)
	s_barrier
	s_cmp_eq_u32 s16, 1
	s_cbranch_scc1 .Lgin_nodma
	s_mov_b32 m0, s22
	s_nop 0
	global_load_lds_dwordx4 v251, s[20:21]
	s_add_u32 m0, m0, 0x1000
	s_add_u32 s20, s20, 0x10000
	s_addc_u32 s21, s21, 0
	global_load_lds_dwordx4 v251, s[20:21]
	s_add_u32 m0, m0, 0x1000
	s_add_u32 s20, s20, 0x10000
	s_addc_u32 s21, s21, 0
	global_load_lds_dwordx4 v251, s[20:21]
	s_add_u32 m0, m0, 0x1000
	s_add_u32 s20, s20, 0x10000
	s_addc_u32 s21, s21, 0
	global_load_lds_dwordx4 v251, s[20:21]
	s_add_u32 m0, m0, 0x1000
	s_add_u32 s20, s20, 0x10000
	s_addc_u32 s21, s21, 0
	global_load_lds_dwordx4 v251, s[20:21]
	s_add_u32 m0, m0, 0x1000
	s_add_u32 s20, s20, 0x10000
	s_addc_u32 s21, s21, 0
	global_load_lds_dwordx4 v251, s[20:21]
	s_add_u32 m0, m0, 0x1000
	s_add_u32 s20, s20, 0x10000
	s_addc_u32 s21, s21, 0
	global_load_lds_dwordx4 v251, s[20:21]
	s_add_u32 m0, m0, 0x1000
	s_add_u32 s20, s20, 0x10000
	s_addc_u32 s21, s21, 0
	global_load_lds_dwordx4 v251, s[20:21]
	s_add_u32 m0, m0, 0x1000
	s_sub_u32 s20, s20, 458624
	s_subb_u32 s21, s21, 0
	global_load_lds_dwordx4 v251, s[24:25]
	s_add_u32 m0, m0, 0x1000
	s_add_u32 s24, s24, 0x10000
	s_addc_u32 s25, s25, 0
	global_load_lds_dwordx4 v251, s[24:25]
	s_add_u32 m0, m0, 0x1000
	s_add_u32 s24, s24, 0x10000
	s_addc_u32 s25, s25, 0
	global_load_lds_dwordx4 v251, s[24:25]
	s_add_u32 m0, m0, 0x1000
	s_add_u32 s24, s24, 0x10000
	s_addc_u32 s25, s25, 0
	global_load_lds_dwordx4 v251, s[24:25]
	s_sub_u32 s24, s24, 196480
	s_subb_u32 s25, s25, 0
.Lgin_nodma:
	v_mfma_f32_32x32x16_bf16 v[0:15], v[216:219], v[128:131], v[0:15]
	v_mfma_f32_32x32x16_bf16 v[16:31], v[232:235], v[128:131], v[16:31]
	v_mfma_f32_32x32x16_bf16 v[32:47], v[216:219], v[148:151], v[32:47]
	v_mfma_f32_32x32x16_bf16 v[48:63], v[232:235], v[148:151], v[48:63]
	v_mfma_f32_32x32x16_bf16 v[64:79], v[216:219], v[164:167], v[64:79]
	v_mfma_f32_32x32x16_bf16 v[80:95], v[232:235], v[164:167], v[80:95]
	v_mfma_f32_32x32x16_bf16 v[96:111], v[216:219], v[180:183], v[96:111]
	v_mfma_f32_32x32x16_bf16 v[112:127], v[232:235], v[180:183], v[112:127]
	v_mfma_f32_32x32x16_bf16 v[0:15], v[220:223], v[132:135], v[0:15]
	v_mfma_f32_32x32x16_bf16 v[16:31], v[236:239], v[132:135], v[16:31]
	v_mfma_f32_32x32x16_bf16 v[32:47], v[220:223], v[152:155], v[32:47]
	v_mfma_f32_32x32x16_bf16 v[48:63], v[236:239], v[152:155], v[48:63]
	v_mfma_f32_32x32x16_bf16 v[64:79], v[220:223], v[168:171], v[64:79]
	v_mfma_f32_32x32x16_bf16 v[80:95], v[236:239], v[168:171], v[80:95]
	v_mfma_f32_32x32x16_bf16 v[96:111], v[220:223], v[184:187], v[96:111]
	v_mfma_f32_32x32x16_bf16 v[112:127], v[236:239], v[184:187], v[112:127]
	v_mfma_f32_32x32x16_bf16 v[0:15], v[224:227], v[136:139], v[0:15]
	v_mfma_f32_32x32x16_bf16 v[16:31], v[240:243], v[136:139], v[16:31]
	v_mfma_f32_32x32x16_bf16 v[32:47], v[224:227], v[156:159], v[32:47]
	v_mfma_f32_32x32x16_bf16 v[48:63], v[240:243], v[156:159], v[48:63]
	v_mfma_f32_32x32x16_bf16 v[64:79], v[224:227], v[172:175], v[64:79]
	v_mfma_f32_32x32x16_bf16 v[80:95], v[240:243], v[172:175], v[80:95]
	v_mfma_f32_32x32x16_bf16 v[96:111], v[224:227], v[188:191], v[96:111]
	v_mfma_f32_32x32x16_bf16 v[112:127], v[240:243], v[188:191], v[112:127]
	v_mfma_f32_32x32x16_bf16 v[0:15], v[228:231], v[140:143], v[0:15]
	v_mfma_f32_32x32x16_bf16 v[16:31], v[244:247], v[140:143], v[16:31]
	v_mfma_f32_32x32x16_bf16 v[32:47], v[228:231], v[160:163], v[32:47]
	v_mfma_f32_32x32x16_bf16 v[48:63], v[244:247], v[160:163], v[48:63]
	v_mfma_f32_32x32x16_bf16 v[64:79], v[228:231], v[176:179], v[64:79]
	v_mfma_f32_32x32x16_bf16 v[80:95], v[244:247], v[176:179], v[80:95]
	v_mfma_f32_32x32x16_bf16 v[96:111], v[228:231], v[212:215], v[96:111]
	v_mfma_f32_32x32x16_bf16 v[112:127], v[244:247], v[212:215], v[112:127]
	s_sub_u32 s16, s16, 1
	s_cmp_lg_u32 s16, 0
	s_cbranch_scc1 .Lgin_k
	s_nop 15
	s_nop 3
	v_and_b32_e32 v215, 31, v193
	v_mul_u32_u24_e32 v212, 0x110, v215
	v_bfe_u32 v215, v193, 5, 1
	v_lshl_add_u32 v212, v215, 3, v212
	v_bfe_u32 v215, v193, 7, 1
	v_mov_b32_e32 v216, 34816
	v_mad_u32_u24 v212, v215, v216, v212
	v_bfe_u32 v215, v193, 6, 1
	v_lshl_add_u32 v212, v215, 7, v212
	v_cvt_pk_bf16_f32 v128, v0, v1
	v_cvt_pk_bf16_f32 v129, v2, v3
	ds_write_b64 v212, v[128:129] offset:0
	v_cvt_pk_bf16_f32 v130, v4, v5
	v_cvt_pk_bf16_f32 v131, v6, v7
	ds_write_b64 v212, v[130:131] offset:16
	v_cvt_pk_bf16_f32 v132, v8, v9
	v_cvt_pk_bf16_f32 v133, v10, v11
	ds_write_b64 v212, v[132:133] offset:32
	v_cvt_pk_bf16_f32 v134, v12, v13
	v_cvt_pk_bf16_f32 v135, v14, v15
	ds_write_b64 v212, v[134:135] offset:48
	v_cvt_pk_bf16_f32 v136, v16, v17
	v_cvt_pk_bf16_f32 v137, v18, v19
	ds_write_b64 v212, v[136:137] offset:64
	v_cvt_pk_bf16_f32 v138, v20, v21
	v_cvt_pk_bf16_f32 v139, v22, v23
	ds_write_b64 v212, v[138:139] offset:80
	v_cvt_pk_bf16_f32 v140, v24, v25
	v_cvt_pk_bf16_f32 v141, v26, v27
	ds_write_b64 v212, v[140:141] offset:96
	v_cvt_pk_bf16_f32 v142, v28, v29
	v_cvt_pk_bf16_f32 v143, v30, v31
	ds_write_b64 v212, v[142:143] offset:112
	v_cvt_pk_bf16_f32 v128, v32, v33
	v_cvt_pk_bf16_f32 v129, v34, v35
	ds_write_b64 v212, v[128:129] offset:8704
	v_cvt_pk_bf16_f32 v130, v36, v37
	v_cvt_pk_bf16_f32 v131, v38, v39
	ds_write_b64 v212, v[130:131] offset:8720
	v_cvt_pk_bf16_f32 v132, v40, v41
	v_cvt_pk_bf16_f32 v133, v42, v43
	ds_write_b64 v212, v[132:133] offset:8736
	v_cvt_pk_bf16_f32 v134, v44, v45
	v_cvt_pk_bf16_f32 v135, v46, v47
	ds_write_b64 v212, v[134:135] offset:8752
	v_cvt_pk_bf16_f32 v136, v48, v49
	v_cvt_pk_bf16_f32 v137, v50, v51
	ds_write_b64 v212, v[136:137] offset:8768
	v_cvt_pk_bf16_f32 v138, v52, v53
	v_cvt_pk_bf16_f32 v139, v54, v55
	ds_write_b64 v212, v[138:139] offset:8784
	v_cvt_pk_bf16_f32 v140, v56, v57
	v_cvt_pk_bf16_f32 v141, v58, v59
	ds_write_b64 v212, v[140:141] offset:8800
	v_cvt_pk_bf16_f32 v142, v60, v61
	v_cvt_pk_bf16_f32 v143, v62, v63
	ds_write_b64 v212, v[142:143] offset:8816
	v_cvt_pk_bf16_f32 v128, v64, v65
	v_cvt_pk_bf16_f32 v129, v66, v67
	ds_write_b64 v212, v[128:129] offset:17408
	v_cvt_pk_bf16_f32 v130, v68, v69
	v_cvt_pk_bf16_f32 v131, v70, v71
	ds_write_b64 v212, v[130:131] offset:17424
	v_cvt_pk_bf16_f32 v132, v72, v73
	v_cvt_pk_bf16_f32 v133, v74, v75
	ds_write_b64 v212, v[132:133] offset:17440
	v_cvt_pk_bf16_f32 v134, v76, v77
	v_cvt_pk_bf16_f32 v135, v78, v79
	ds_write_b64 v212, v[134:135] offset:17456
	v_cvt_pk_bf16_f32 v136, v80, v81
	v_cvt_pk_bf16_f32 v137, v82, v83
	ds_write_b64 v212, v[136:137] offset:17472
	v_cvt_pk_bf16_f32 v138, v84, v85
	v_cvt_pk_bf16_f32 v139, v86, v87
	ds_write_b64 v212, v[138:139] offset:17488
	v_cvt_pk_bf16_f32 v140, v88, v89
	v_cvt_pk_bf16_f32 v141, v90, v91
	ds_write_b64 v212, v[140:141] offset:17504
	v_cvt_pk_bf16_f32 v142, v92, v93
	v_cvt_pk_bf16_f32 v143, v94, v95
	ds_write_b64 v212, v[142:143] offset:17520
	v_cvt_pk_bf16_f32 v128, v96, v97
	v_cvt_pk_bf16_f32 v129, v98, v99
	ds_write_b64 v212, v[128:129] offset:26112
	v_cvt_pk_bf16_f32 v130, v100, v101
	v_cvt_pk_bf16_f32 v131, v102, v103
	ds_write_b64 v212, v[130:131] offset:26128
	v_cvt_pk_bf16_f32 v132, v104, v105
	v_cvt_pk_bf16_f32 v133, v106, v107
	ds_write_b64 v212, v[132:133] offset:26144
	v_cvt_pk_bf16_f32 v134, v108, v109
	v_cvt_pk_bf16_f32 v135, v110, v111
	ds_write_b64 v212, v[134:135] offset:26160
	v_cvt_pk_bf16_f32 v136, v112, v113
	v_cvt_pk_bf16_f32 v137, v114, v115
	ds_write_b64 v212, v[136:137] offset:26176
	v_cvt_pk_bf16_f32 v138, v116, v117
	v_cvt_pk_bf16_f32 v139, v118, v119
	ds_write_b64 v212, v[138:139] offset:26192
	v_cvt_pk_bf16_f32 v140, v120, v121
	v_cvt_pk_bf16_f32 v141, v122, v123
	ds_write_b64 v212, v[140:141] offset:26208
	v_cvt_pk_bf16_f32 v142, v124, v125
	v_cvt_pk_bf16_f32 v143, v126, v127
	ds_write_b64 v212, v[142:143] offset:26224
	s_waitcnt lgkmcnt(0)
	s_barrier
	v_lshrrev_b32_e32 v215, 4, v193
	v_and_b32_e32 v216, 15, v193
	v_mul_u32_u24_e32 v213, 0x110, v215
	v_lshl_add_u32 v213, v216, 4, v213
	v_mul_lo_u32 v214, v215, s12
	v_lshl_add_u32 v214, v216, 4, v214
	s_lshl_b32 s28, s12, 4
	ds_read_b128 v[148:151], v213 offset:0
	ds_read_b128 v[152:155], v213 offset:4352
	ds_read_b128 v[156:159], v213 offset:8704
	ds_read_b128 v[160:163], v213 offset:13056
	ds_read_b128 v[164:167], v213 offset:17408
	ds_read_b128 v[168:171], v213 offset:21760
	ds_read_b128 v[172:175], v213 offset:26112
	ds_read_b128 v[176:179], v213 offset:30464
	ds_read_b128 v[180:183], v213 offset:34816
	ds_read_b128 v[184:187], v213 offset:39168
	ds_read_b128 v[188:191], v213 offset:43520
	ds_read_b128 v[220:223], v213 offset:47872
	ds_read_b128 v[224:227], v213 offset:52224
	ds_read_b128 v[228:231], v213 offset:56576
	ds_read_b128 v[232:235], v213 offset:60928
	ds_read_b128 v[236:239], v213 offset:65280
	s_waitcnt lgkmcnt(15)
	global_store_dwordx4 v214, v[148:151], s[26:27]
	s_add_u32 s26, s26, s28
	s_addc_u32 s27, s27, 0
	s_waitcnt lgkmcnt(14)
	global_store_dwordx4 v214, v[152:155], s[26:27]
	s_add_u32 s26, s26, s28
	s_addc_u32 s27, s27, 0
	s_waitcnt lgkmcnt(13)
	global_store_dwordx4 v214, v[156:159], s[26:27]
	s_add_u32 s26, s26, s28
	s_addc_u32 s27, s27, 0
	s_waitcnt lgkmcnt(12)
	global_store_dwordx4 v214, v[160:163], s[26:27]
	s_add_u32 s26, s26, s28
	s_addc_u32 s27, s27, 0
	s_waitcnt lgkmcnt(11)
	global_store_dwordx4 v214, v[164:167], s[26:27]
	s_add_u32 s26, s26, s28
	s_addc_u32 s27, s27, 0
	s_waitcnt lgkmcnt(10)
	global_store_dwordx4 v214, v[168:171], s[26:27]
	s_add_u32 s26, s26, s28
	s_addc_u32 s27, s27, 0
	s_waitcnt lgkmcnt(9)
	global_store_dwordx4 v214, v[172:175], s[26:27]
	s_add_u32 s26, s26, s28
	s_addc_u32 s27, s27, 0
	s_waitcnt lgkmcnt(8)
	global_store_dwordx4 v214, v[176:179], s[26:27]
	s_add_u32 s26, s26, s28
	s_addc_u32 s27, s27, 0
	s_waitcnt lgkmcnt(7)
	global_store_dwordx4 v214, v[180:183], s[26:27]
	s_add_u32 s26, s26, s28
	s_addc_u32 s27, s27, 0
	s_waitcnt lgkmcnt(6)
	global_store_dwordx4 v214, v[184:187], s[26:27]
	s_add_u32 s26, s26, s28
	s_addc_u32 s27, s27, 0
	s_waitcnt lgkmcnt(5)
	global_store_dwordx4 v214, v[188:191], s[26:27]
	s_add_u32 s26, s26, s28
	s_addc_u32 s27, s27, 0
	s_waitcnt lgkmcnt(4)
	global_store_dwordx4 v214, v[220:223], s[26:27]
	s_add_u32 s26, s26, s28
	s_addc_u32 s27, s27, 0
	s_waitcnt lgkmcnt(3)
	global_store_dwordx4 v214, v[224:227], s[26:27]
	s_add_u32 s26, s26, s28
	s_addc_u32 s27, s27, 0
	s_waitcnt lgkmcnt(2)
	global_store_dwordx4 v214, v[228:231], s[26:27]
	s_add_u32 s26, s26, s28
	s_addc_u32 s27, s27, 0
	s_waitcnt lgkmcnt(1)
	global_store_dwordx4 v214, v[232:235], s[26:27]
	s_add_u32 s26, s26, s28
	s_addc_u32 s27, s27, 0
	s_waitcnt lgkmcnt(0)
	global_store_dwordx4 v214, v[236:239], s[26:27]
	s_barrier
	s_add_u32 s0, s0, s6
	s_cmp_lt_u32 s0, s1
	s_cbranch_scc1 .Lgin_tile
.Lgin_done:
	v_mov_b32_e32 v243, 0x13c00
